# NSA selected branch fast path: next-tile LDS staging writes interleaved with the last head's PV MFMAs
# speedup vs baseline: 1.0115x; 1.0115x over previous
; DI void nsa_item(const Params& p, int bk, int qb, char* smem, float Mb) {
;     ...
;             lstore(bsel ^ 1);
;             __syncthreads();
;             bsel ^= 1; j = jn; m = mn;
;         }
.Lsel_bot2:
	v_readlane_b32 s2, v249, 29
	s_nop 1
	v_lshl_add_u32 v72, v242, 3, s2
	ds_read_b64 v[72:73], v72
	v_mov_b32_e32 v245, v242
	v_mov_b64_e32 v[88:89], v[208:209]
	s_waitcnt lgkmcnt(0)
	s_barrier
	s_andn2_b64 exec, exec, s[10:11]
	s_cbranch_execz .LBB0_559

; DI void nsa_item(const Params& p, int bk, int qb, char* smem, float Mb) {
;     ...
;                 for (int k4 = 0; k4 < 4; ++k4) {
;                     kf[k4][0] = *(const bf16x8*)(kb_ + k4 * 16 * 144); kf[k4][1] = *(const bf16x8*)(kb_ + k4 * 16 * 144 + 64);
;                     vf[k4][0] = *(const bf16x8*)(kb_ + 9216 + k4 * 16 * 144); vf[k4][1] = *(const bf16x8*)(kb_ + 9216 + k4 * 16 * 144 + 64);
;                 }
;                 const bool mine = (sub >> fr) & 1u;
;                 const float Ml = mine ? Mb : 3.0e38f;
;                 const bool diag = (j == cur);
; #pragma unroll
;                 for (int g = 0; g < 3; ++g) {
;                     f32x4 st[4];
;                     st_from(kf, qf[g], st, -Ml);
;                     if (diag) {
; #pragma unroll
;                         for (int k4 = 0; k4 < 4; ++k4)
; #pragma unroll
;                             for (int ii = 0; ii < 4; ++ii) {
;                                 const float pv = (j * 64 + k4 * 16 + fq * 4 + ii <= tq) ? __builtin_amdgcn_exp2f(st[k4][ii]) : 0.f;
;                                 st[k4][ii] = pv; ls[g] += pv;
;                             }
;                     } else {
; #pragma unroll
;                         for (int k4 = 0; k4 < 4; ++k4)
; #pragma unroll
;                             for (int ii = 0; ii < 4; ++ii) { const float pv = __builtin_amdgcn_exp2f(st[k4][ii]); st[k4][ii] = pv; ls[g] += pv; }
;                     }
;                     pv_from(vf, st, o[g]);
.Lsel_fast:
	ds_read_b128 v[140:143], v116 offset:6976
	ds_read_b128 v[108:111], v116 offset:9216
	ds_read_b128 v[88:91], v116 offset:9280
	ds_read_b128 v[92:95], v116 offset:11520
	ds_read_b128 v[96:99], v116 offset:11584
	ds_read_b128 v[100:103], v116 offset:13824
	ds_read_b128 v[104:107], v116 offset:13888
	ds_read_b128 v[112:115], v116 offset:16128
	s_waitcnt lgkmcnt(7)
	ds_read_b128 v[116:119], v116 offset:16192
	v_mfma_f32_16x16x32_bf16 v[156:159], v[120:123], v[0:3], v[124:127]
	v_mfma_f32_16x16x32_bf16 v[164:167], v[132:135], v[0:3], v[124:127]
	v_mfma_f32_16x16x32_bf16 v[172:175], v[144:147], v[0:3], v[124:127]
	v_mfma_f32_16x16x32_bf16 v[180:183], v[152:155], v[0:3], v[124:127]
	v_mfma_f32_16x16x32_bf16 v[156:159], v[128:131], v[4:7], v[156:159]
	v_mfma_f32_16x16x32_bf16 v[164:167], v[136:139], v[4:7], v[164:167]
	v_mfma_f32_16x16x32_bf16 v[172:175], v[148:151], v[4:7], v[172:175]
	v_mfma_f32_16x16x32_bf16 v[180:183], v[140:143], v[4:7], v[180:183]
	v_mfma_f32_16x16x32_bf16 v[184:187], v[120:123], v[8:11], v[124:127]
	v_mfma_f32_16x16x32_bf16 v[176:179], v[132:135], v[8:11], v[124:127]
	v_mfma_f32_16x16x32_bf16 v[168:171], v[144:147], v[8:11], v[124:127]
	v_mfma_f32_16x16x32_bf16 v[160:163], v[152:155], v[8:11], v[124:127]
	s_nop 1
	v_mfma_f32_16x16x32_bf16 v[184:187], v[128:131], v[12:15], v[184:187]
	v_exp_f32_e32 v156, v156
	v_exp_f32_e32 v157, v157
	v_exp_f32_e32 v158, v158
	v_exp_f32_e32 v159, v159
	v_mfma_f32_16x16x32_bf16 v[176:179], v[136:139], v[12:15], v[176:179]
	v_exp_f32_e32 v164, v164
	v_exp_f32_e32 v165, v165
	v_exp_f32_e32 v166, v166
	v_exp_f32_e32 v167, v167
	v_mfma_f32_16x16x32_bf16 v[168:171], v[148:151], v[12:15], v[168:171]
	v_exp_f32_e32 v172, v172
	v_exp_f32_e32 v173, v173
	v_exp_f32_e32 v174, v174
	v_exp_f32_e32 v175, v175
	v_mfma_f32_16x16x32_bf16 v[160:163], v[140:143], v[12:15], v[160:163]
	v_exp_f32_e32 v180, v180
	v_exp_f32_e32 v181, v181
	v_exp_f32_e32 v182, v182
	v_exp_f32_e32 v183, v183
	v_pk_add_f32 v[254:255], v[156:157], v[158:159]
	v_pk_add_f32 v[254:255], v[254:255], v[164:165]
	v_pk_add_f32 v[254:255], v[254:255], v[166:167]
	v_cvt_pk_bf16_f32 v156, v156, v157
	v_cvt_pk_bf16_f32 v157, v158, v159
	v_cvt_pk_bf16_f32 v158, v164, v165
	v_cvt_pk_bf16_f32 v159, v166, v167
	v_pk_add_f32 v[164:165], v[172:173], v[174:175]
	v_pk_add_f32 v[164:165], v[164:165], v[180:181]
	v_pk_add_f32 v[164:165], v[164:165], v[182:183]
	v_cvt_pk_bf16_f32 v172, v172, v173
	v_cvt_pk_bf16_f32 v173, v174, v175
	v_cvt_pk_bf16_f32 v174, v180, v181
	v_cvt_pk_bf16_f32 v175, v182, v183
	v_pk_add_f32 v[254:255], v[254:255], v[164:165]
	v_add_f32_e32 v244, v244, v254
	v_add_f32_e32 v244, v244, v255
	s_waitcnt lgkmcnt(0)
; DI void nsa_item(const Params& p, int bk, int qb, char* smem, float Mb) {
;     ...
;             for (int i = 0; i < 4; ++i) *(u32x4*)(tb + bsel * 18432 + (i >> 1) * 9216 + (l_row + 32 * (i & 1)) * 144 + l_cc * 16) = rg[i];
;     ...
;                 for (int g = 0; g < 3; ++g) {
;                     f32x4 st[4];
;                     st_from(kf, qf[g], st, -Ml);
;                     if (diag) {
; #pragma unroll
;                         for (int k4 = 0; k4 < 4; ++k4)
; #pragma unroll
;                             for (int ii = 0; ii < 4; ++ii) {
;                                 const float pv = (j * 64 + k4 * 16 + fq * 4 + ii <= tq) ? __builtin_amdgcn_exp2f(st[k4][ii]) : 0.f;
;                                 st[k4][ii] = pv; ls[g] += pv;
;                             }
;                     } else {
; #pragma unroll
;                         for (int k4 = 0; k4 < 4; ++k4)
; #pragma unroll
;                             for (int ii = 0; ii < 4; ++ii) { const float pv = __builtin_amdgcn_exp2f(st[k4][ii]); st[k4][ii] = pv; ls[g] += pv; }
;                     }
;                     pv_from(vf, st, o[g]);
;                 }
;             }
;             lstore(bsel ^ 1);
;             __syncthreads();
;             bsel ^= 1; j = jn; m = mn;
	s_nop 1
	v_mfma_f32_16x16x32_bf16 v[68:71], v[108:111], v[156:159], v[68:71]
	v_exp_f32_e32 v184, v184
	v_mfma_f32_16x16x32_bf16 v[64:67], v[92:95], v[156:159], v[64:67]
	v_exp_f32_e32 v185, v185
	v_mfma_f32_16x16x32_bf16 v[60:63], v[100:103], v[156:159], v[60:63]
	v_exp_f32_e32 v186, v186
	v_mfma_f32_16x16x32_bf16 v[56:59], v[112:115], v[156:159], v[56:59]
	v_exp_f32_e32 v187, v187
	v_mfma_f32_16x16x32_bf16 v[68:71], v[88:91], v[172:175], v[68:71]
	v_exp_f32_e32 v176, v176
	v_mfma_f32_16x16x32_bf16 v[64:67], v[96:99], v[172:175], v[64:67]
	v_exp_f32_e32 v177, v177
	v_mfma_f32_16x16x32_bf16 v[60:63], v[104:107], v[172:175], v[60:63]
	v_exp_f32_e32 v178, v178
	v_mfma_f32_16x16x32_bf16 v[56:59], v[116:119], v[172:175], v[56:59]
	v_exp_f32_e32 v179, v179
	v_mfma_f32_16x16x32_bf16 v[156:159], v[120:123], v[16:19], v[124:127]
	v_exp_f32_e32 v168, v168
	v_mfma_f32_16x16x32_bf16 v[164:167], v[132:135], v[16:19], v[124:127]
	v_exp_f32_e32 v169, v169
	v_mfma_f32_16x16x32_bf16 v[172:175], v[144:147], v[16:19], v[124:127]
	v_exp_f32_e32 v170, v170
	v_mfma_f32_16x16x32_bf16 v[180:183], v[152:155], v[16:19], v[124:127]
	v_exp_f32_e32 v171, v171
	v_mfma_f32_16x16x32_bf16 v[156:159], v[128:131], v[20:23], v[156:159]
	v_exp_f32_e32 v160, v160
	v_mfma_f32_16x16x32_bf16 v[164:167], v[136:139], v[20:23], v[164:167]
	v_exp_f32_e32 v161, v161
	v_mfma_f32_16x16x32_bf16 v[172:175], v[148:151], v[20:23], v[172:175]
	v_exp_f32_e32 v162, v162
	v_mfma_f32_16x16x32_bf16 v[180:183], v[140:143], v[20:23], v[180:183]
	v_exp_f32_e32 v163, v163
	v_pk_add_f32 v[254:255], v[184:185], v[186:187]
	v_pk_add_f32 v[254:255], v[254:255], v[176:177]
	v_pk_add_f32 v[254:255], v[254:255], v[178:179]
	v_cvt_pk_bf16_f32 v184, v184, v185
	v_cvt_pk_bf16_f32 v185, v186, v187
	v_cvt_pk_bf16_f32 v186, v176, v177
	v_cvt_pk_bf16_f32 v187, v178, v179
	v_pk_add_f32 v[176:177], v[168:169], v[170:171]
	v_pk_add_f32 v[176:177], v[176:177], v[160:161]
	v_pk_add_f32 v[176:177], v[176:177], v[162:163]
	v_cvt_pk_bf16_f32 v168, v168, v169
	v_cvt_pk_bf16_f32 v169, v170, v171
	v_cvt_pk_bf16_f32 v170, v160, v161
	v_cvt_pk_bf16_f32 v171, v162, v163
	v_pk_add_f32 v[254:255], v[254:255], v[176:177]
	v_add_f32_e32 v243, v243, v254
	v_add_f32_e32 v243, v243, v255
	s_nop 1
	v_mfma_f32_16x16x32_bf16 v[52:55], v[108:111], v[184:187], v[52:55]
	v_exp_f32_e32 v156, v156
	v_exp_f32_e32 v157, v157
	v_mfma_f32_16x16x32_bf16 v[48:51], v[92:95], v[184:187], v[48:51]
	v_exp_f32_e32 v158, v158
	v_exp_f32_e32 v159, v159
	v_mfma_f32_16x16x32_bf16 v[44:47], v[100:103], v[184:187], v[44:47]
	v_exp_f32_e32 v164, v164
	v_exp_f32_e32 v165, v165
	v_mfma_f32_16x16x32_bf16 v[40:43], v[112:115], v[184:187], v[40:43]
	v_exp_f32_e32 v166, v166
	v_exp_f32_e32 v167, v167
	v_mfma_f32_16x16x32_bf16 v[52:55], v[88:91], v[168:171], v[52:55]
	v_exp_f32_e32 v172, v172
	v_exp_f32_e32 v173, v173
	v_mfma_f32_16x16x32_bf16 v[48:51], v[96:99], v[168:171], v[48:51]
	v_exp_f32_e32 v174, v174
	v_exp_f32_e32 v175, v175
	v_mfma_f32_16x16x32_bf16 v[44:47], v[104:107], v[168:171], v[44:47]
	v_exp_f32_e32 v180, v180
	v_exp_f32_e32 v181, v181
	v_mfma_f32_16x16x32_bf16 v[40:43], v[116:119], v[168:171], v[40:43]
	v_exp_f32_e32 v182, v182
	v_exp_f32_e32 v183, v183
	v_pk_add_f32 v[254:255], v[156:157], v[158:159]
	v_pk_add_f32 v[254:255], v[254:255], v[164:165]
	v_pk_add_f32 v[254:255], v[254:255], v[166:167]
	v_cvt_pk_bf16_f32 v156, v156, v157
	v_cvt_pk_bf16_f32 v157, v158, v159
	v_cvt_pk_bf16_f32 v158, v164, v165
	v_cvt_pk_bf16_f32 v159, v166, v167
	v_pk_add_f32 v[164:165], v[172:173], v[174:175]
	v_pk_add_f32 v[164:165], v[164:165], v[180:181]
	v_pk_add_f32 v[164:165], v[164:165], v[182:183]
	v_cvt_pk_bf16_f32 v172, v172, v173
	v_cvt_pk_bf16_f32 v173, v174, v175
	v_cvt_pk_bf16_f32 v174, v180, v181
	v_cvt_pk_bf16_f32 v175, v182, v183
	v_pk_add_f32 v[254:255], v[254:255], v[164:165]
	v_add_f32_e32 v241, v241, v254
	v_add_f32_e32 v241, v241, v255
	s_or_b64 exec, exec, s[12:13]
	s_and_b64 s[4:5], exec, s[4:5]
	s_or_b64 s[10:11], s[4:5], s[10:11]
	s_xor_b32 s22, s22, 1
	s_mul_i32 s4, s22, 0x4800
	v_add_u32_e32 v254, s4, v195
	s_waitcnt vmcnt(3)
	ds_write_b128 v254, v[72:75]
	v_mfma_f32_16x16x32_bf16 v[36:39], v[108:111], v[156:159], v[36:39]
	v_mfma_f32_16x16x32_bf16 v[32:35], v[92:95], v[156:159], v[32:35]
	s_waitcnt vmcnt(2)
	ds_write_b128 v254, v[76:79] offset:4608
	v_mfma_f32_16x16x32_bf16 v[28:31], v[100:103], v[156:159], v[28:31]
	v_mfma_f32_16x16x32_bf16 v[24:27], v[112:115], v[156:159], v[24:27]
	s_waitcnt vmcnt(1)
	ds_write_b128 v254, v[80:83] offset:9216
	v_mfma_f32_16x16x32_bf16 v[36:39], v[88:91], v[172:175], v[36:39]
	v_mfma_f32_16x16x32_bf16 v[32:35], v[96:99], v[172:175], v[32:35]
	s_waitcnt vmcnt(0)
	ds_write_b128 v254, v[84:87] offset:13824
	v_mfma_f32_16x16x32_bf16 v[28:31], v[104:107], v[172:175], v[28:31]
	v_mfma_f32_16x16x32_bf16 v[24:27], v[116:119], v[172:175], v[24:27]
	s_branch .Lsel_bot2
